# stack of the individually validated small edits: sample-unit load hoists, attention Q prefetch, 912 weight items moved to P1 idle workgroups, always-true bounds checks removed
# speedup vs baseline: 1.0052x; 1.0052x over previous
.LBB0_707:
	v_mov_b32_e32 v169, v153
	v_mov_b32_e32 v148, v162
	v_mov_b32_e32 v168, v150
	v_mov_b32_e32 v149, 0
	s_waitcnt vmcnt(1)
	v_add_f32_e32 v18, v154, v18
	v_mul_f32_e64 v19, |v18|, s36
	v_exp_f32_e32 v19, v19
	v_max_f32_e32 v24, 0, v18
	v_add_f32_e32 v19, 1.0, v19
	v_log_f32_e32 v19, v19
	s_nop 0
	v_fmac_f32_e32 v24, 0x3f317218, v19
	s_add_i32 s67, s82, 64
	s_waitcnt vmcnt(1)
	v_add_u32_e32 v18, s67, v148
	v_cmp_gt_i32_e32 vcc, s59, v18
	s_and_saveexec_b64 s[34:35], vcc
	s_cbranch_execz .LBB0_711
	global_load_dword v149, v[208:209], off
	v_lshl_add_u64 v[208:209], v[208:209], 0, s[100:101]

.LBB0_738:
	s_waitcnt lgkmcnt(0)
	s_barrier
	s_waitcnt lgkmcnt(0)
	s_barrier
	s_mov_b64 s[70:71], exec
	ds_read_b128 v[34:37], v216
	ds_read_b128 v[38:41], v217
	ds_read_b128 v[42:45], v217 offset:16
	v_cmp_lt_i32_e32 vcc, 31, v146
	s_waitcnt lgkmcnt(1)
	v_pk_add_f32 v[36:37], v[36:37], v[40:41]
	v_pk_add_f32 v[40:41], v[34:35], v[38:39]
	ds_read_b128 v[46:49], v218
	s_waitcnt lgkmcnt(0)
	v_pk_add_f32 v[34:35], v[48:49], v[44:45]
	v_pk_add_f32 v[38:39], v[46:47], v[42:43]
	s_and_saveexec_b64 s[34:35], vcc
	s_cbranch_execz .LBB0_741
	ds_read_b128 v[42:45], v219
	s_waitcnt lgkmcnt(0)
	v_lshlrev_b32_e32 v46, 16, v42
	v_and_b32_e32 v47, 0xffff0000, v42
	v_lshlrev_b32_e32 v42, 16, v43
	v_and_b32_e32 v43, 0xffff0000, v43
	v_pk_add_f32 v[36:37], v[36:37], v[42:43]
	v_lshlrev_b32_e32 v42, 16, v44
	v_and_b32_e32 v43, 0xffff0000, v44
	v_lshlrev_b32_e32 v44, 16, v45
	v_and_b32_e32 v45, 0xffff0000, v45
	v_pk_add_f32 v[40:41], v[40:41], v[46:47]
	v_pk_add_f32 v[34:35], v[34:35], v[44:45]
	v_pk_add_f32 v[38:39], v[38:39], v[42:43]
.LBB0_741:
	s_or_b64 exec, exec, s[34:35]
	s_waitcnt vmcnt(0)
	v_lshlrev_b32_e32 v42, 16, v118
	v_and_b32_e32 v43, 0xffff0000, v118
	v_mul_f32_e32 v44, 0xbfb8aa3b, v42
	v_mul_f32_e32 v45, 0xbfb8aa3b, v43
	v_exp_f32_e32 v44, v44
	v_exp_f32_e32 v45, v45
	v_add_f32_e32 v44, 1.0, v44
	v_add_f32_e32 v45, 1.0, v45
	v_rcp_f32_e32 v44, v44
	v_rcp_f32_e32 v45, v45
	s_nop 0
	v_pk_mul_f32 v[42:43], v[44:45], v[42:43]
	v_and_b32_e32 v45, 0xffff0000, v119
	v_lshlrev_b32_e32 v44, 16, v119
	v_mul_f32_e32 v46, 0xbfb8aa3b, v44
	v_mul_f32_e32 v47, 0xbfb8aa3b, v45
	v_exp_f32_e32 v46, v46
	v_exp_f32_e32 v47, v47
	v_pk_mul_f32 v[40:41], v[42:43], v[40:41]
	v_add_f32_e32 v46, 1.0, v46
	v_add_f32_e32 v47, 1.0, v47
	v_rcp_f32_e32 v46, v46
	v_rcp_f32_e32 v47, v47
	v_pk_mul_f32 v[42:43], v[40:41], v[40:41]
	v_cvt_pk_bf16_f32 v126, v40, v41
	v_add_f32_e32 v42, v42, v43
	v_pk_mul_f32 v[44:45], v[46:47], v[44:45]
	v_and_b32_e32 v47, 0xffff0000, v120
	v_lshlrev_b32_e32 v46, 16, v120
	v_mul_f32_e32 v48, 0xbfb8aa3b, v46
	v_mul_f32_e32 v49, 0xbfb8aa3b, v47
	v_exp_f32_e32 v48, v48
	v_exp_f32_e32 v49, v49
	v_pk_mul_f32 v[36:37], v[44:45], v[36:37]
	v_add_f32_e32 v48, 1.0, v48
	v_add_f32_e32 v49, 1.0, v49
	v_rcp_f32_e32 v48, v48
	v_rcp_f32_e32 v49, v49
	v_pk_mul_f32 v[44:45], v[36:37], v[36:37]
	v_cvt_pk_bf16_f32 v127, v36, v37
	v_add_f32_e32 v42, v44, v42
	v_pk_mul_f32 v[46:47], v[48:49], v[46:47]
	v_lshlrev_b32_e32 v48, 16, v121
	v_mul_f32_e32 v51, 0xbfb8aa3b, v48
	v_exp_f32_e32 v51, v51
	v_and_b32_e32 v49, 0xffff0000, v121
	v_pk_mul_f32 v[38:39], v[46:47], v[38:39]
	v_add_f32_e32 v42, v45, v42
	v_add_f32_e32 v51, 1.0, v51
	v_rcp_f32_e32 v52, v51
	v_mul_f32_e32 v51, 0xbfb8aa3b, v49
	v_exp_f32_e32 v51, v51
	v_pk_mul_f32 v[46:47], v[38:39], v[38:39]
	v_cvt_pk_bf16_f32 v128, v38, v39
	v_add_f32_e32 v42, v46, v42
	v_add_f32_e32 v51, 1.0, v51
	v_rcp_f32_e32 v53, v51
	v_add_f32_e32 v42, v47, v42
	v_pk_mul_f32 v[48:49], v[52:53], v[48:49]
	s_nop 0
	v_pk_mul_f32 v[34:35], v[48:49], v[34:35]
	s_nop 0
	v_pk_mul_f32 v[48:49], v[34:35], v[34:35]
	v_cvt_pk_bf16_f32 v129, v34, v35
	v_add_f32_e32 v42, v48, v42
	v_add_f32_e32 v42, v49, v42
	s_nop 1
	v_add_f32_dpp v34, v42, v42 row_shl:4 row_mask:0xf bank_mask:0xf bound_ctrl:1
	s_nop 1
	v_add_f32_dpp v34, v34, v34 row_shl:2 row_mask:0xf bank_mask:0xf bound_ctrl:1
	s_nop 1
	v_add_f32_dpp v166, v34, v34 row_shl:1 row_mask:0xf bank_mask:0xf bound_ctrl:1
	s_xor_b32 s66, s66, 1
	s_and_b64 vcc, exec, s[68:69]
	s_cbranch_vccnz .LBB0_744
	s_waitcnt vmcnt(0)
	v_mov_b64_e32 v[118:119], v[122:123]
	v_mov_b32_e32 v18, v149
	v_mov_b64_e32 v[120:121], v[124:125]
	s_mov_b32 s82, s67
	s_branch .LBB0_707
